# scan1: per-wave alternation of unit kind (transition-matrix vs local-state chunk pass) to balance SIMD load
# speedup vs baseline: 1.1039x; 1.0150x over previous
.LBB0_627:
	s_add_u32 s10, s54, s0
	s_addc_u32 s11, s55, s1
	s_lshl_b32 s0, s93, 5
	s_add_i32 s0, s33, s0
	s_ashr_i32 s1, s0, 31
	s_lshl_b64 s[0:1], s[0:1], 14
	s_add_u32 s0, s10, s0
	s_addc_u32 s1, s11, s1
	v_lshl_add_u64 v[0:1], s[0:1], 0, v[154:155]
	s_waitcnt vmcnt(24)
	v_mov_b32_e32 v163, v155
	s_waitcnt vmcnt(23)
	v_mov_b32_e32 v165, v155
	s_add_i32 s28, s28, s34
	s_xor_b32 s28, s28, 1
	s_not_b64 s[4:5], s[4:5]
	v_lshl_add_u64 v[2:3], v[0:1], 0, v[162:163]
	v_mov_b32_e32 v110, v30
	v_mov_b32_e32 v111, v31
	v_lshl_add_u64 v[0:1], v[0:1], 0, v[164:165]
	v_mov_b32_e32 v126, v14
	v_mov_b32_e32 v127, v15
	v_mov_b32_e32 v78, v46
	v_mov_b32_e32 v79, v47
	v_mov_b32_e32 v94, v62
	v_mov_b32_e32 v95, v63
	s_cmpk_lt_i32 s28, 0xf80
	global_store_dwordx4 v[2:3], v[96:99], off
	global_store_dwordx4 v[2:3], v[100:103], off offset:32
	global_store_dwordx4 v[2:3], v[104:107], off offset:64
	global_store_dwordx4 v[2:3], v[108:111], off offset:96
	global_store_dwordx4 v[0:1], v[112:115], off
	global_store_dwordx4 v[0:1], v[116:119], off offset:32
	global_store_dwordx4 v[0:1], v[120:123], off offset:64
	global_store_dwordx4 v[0:1], v[124:127], off offset:96
	global_store_dwordx4 v[2:3], v[64:67], off offset:128
	global_store_dwordx4 v[2:3], v[68:71], off offset:160
	global_store_dwordx4 v[2:3], v[72:75], off offset:192
	global_store_dwordx4 v[2:3], v[76:79], off offset:224
	global_store_dwordx4 v[0:1], v[80:83], off offset:128
	global_store_dwordx4 v[0:1], v[84:87], off offset:160
	global_store_dwordx4 v[0:1], v[88:91], off offset:192
	global_store_dwordx4 v[0:1], v[92:95], off offset:224
	s_cbranch_scc0 .LBB0_639
